# march v4 + pipelined combine phase
# speedup vs baseline: 1.0749x; 1.0081x over previous
.LBB0_236:
	s_mov_b32 s87, s12
	s_lshl_b64 s[4:5], s[86:87], 4
	s_add_u32 s4, s60, s4
	s_addc_u32 s5, s61, s5
	s_load_dwordx4 s[96:99], s[4:5], 0xc0
	s_mov_b64 s[4:5], -1
	s_waitcnt lgkmcnt(0)
	s_ashr_i32 s42, s97, 1
	s_cmp_lt_i32 s96, 3
	s_cbranch_scc1 .LBB0_327
	s_cmp_lt_i32 s96, 4
	s_cbranch_scc1 .LBB0_311
	s_cmp_lt_i32 s96, 5
	s_cbranch_scc1 .LBB0_245
	s_cmp_eq_u32 s96, 5
	s_cbranch_scc0 .LBB0_244
	v_lshrrev_b32_e32 v1, 6, v175
	v_readlane_b32 s3, v253, 4
	v_readfirstlane_b32 s43, v1
	s_nop 3
	s_add_u32 s18, s3, s43
	v_readlane_b32 s4, v254, 18
	v_readlane_b32 s5, v254, 19
	v_readlane_b32 s6, v254, 16
	v_readlane_b32 s7, v254, 17
	s_lshl_b32 s8, s42, 13
	s_add_u32 s4, s4, s8
	s_addc_u32 s5, s5, 0
	s_lshl_b32 s8, s42, 7
	s_add_u32 s6, s6, s8
	s_addc_u32 s7, s7, 0
	v_and_b32_e32 v2, 31, v175
	v_bfe_u32 v3, v175, 5, 1
	s_lshl_b32 s8, s18, 1
	s_and_b32 s8, s8, 6
	v_or_b32_e32 v3, s8, v3
	v_lshlrev_b32_e32 v46, 3, v2
	v_lshl_or_b32 v46, v3, 8, v46
	v_lshlrev_b32_e32 v100, 1, v46
	v_lshrrev_b32_e32 v47, 5, v46
	v_and_b32_e32 v48, 3, v2
	v_lshlrev_b32_e32 v48, 4, v48
	v_lshl_or_b32 v101, v47, 20, v48
	v_lshlrev_b32_e32 v47, 2, v46
	global_load_dwordx4 v[36:39], v47, s[4:5]
	global_load_dwordx4 v[40:43], v47, s[4:5] offset:16
	v_lshrrev_b32_e32 v48, 3, v2
	v_lshl_or_b32 v48, v3, 2, v48
	v_lshlrev_b32_e32 v48, 2, v48
	global_load_dword v44, v48, s[6:7]
	s_lshr_b32 s43, s18, 2
	s_lshl_b32 s3, s43, 12
	s_add_u32 s4, s48, s3
	s_addc_u32 s5, s49, 0
	s_add_u32 s6, s52, s3
	s_addc_u32 s7, s53, 0
	s_add_u32 s8, s50, s3
	s_addc_u32 s9, s51, 0
	s_lshl_b32 s3, s43, 6
	s_add_u32 s14, s46, s3
	s_addc_u32 s15, s47, 0
	s_lshl_b32 s16, s28, 10
	s_lshl_b32 s17, s28, 4
	s_mov_b32 vcc_lo, s8
	s_mov_b32 vcc_hi, s9
	global_load_dwordx4 v[4:7], v100, s[4:5] nt
	global_load_dwordx4 v[8:11], v100, s[6:7] nt
	global_load_dwordx4 v[12:15], v100, vcc
	global_load_dwordx4 v[16:19], v101, s[14:15]
	s_add_u32 s4, s4, s16
	s_addc_u32 s5, s5, 0
	s_add_u32 s6, s6, s16
	s_addc_u32 s7, s7, 0
	s_add_u32 vcc_lo, vcc_lo, s16
	s_addc_u32 vcc_hi, vcc_hi, 0
	s_add_u32 s14, s14, s17
	s_addc_u32 s15, s15, 0
	global_load_dwordx4 v[20:23], v100, s[4:5] nt
	global_load_dwordx4 v[24:27], v100, s[6:7] nt
	global_load_dwordx4 v[28:31], v100, vcc
	global_load_dwordx4 v[32:35], v101, s[14:15]
	s_add_u32 s4, s4, s16
	s_addc_u32 s5, s5, 0
	s_add_u32 s6, s6, s16
	s_addc_u32 s7, s7, 0
	s_add_u32 vcc_lo, vcc_lo, s16
	s_addc_u32 vcc_hi, vcc_hi, 0
	s_add_u32 s14, s14, s17
	s_addc_u32 s15, s15, 0
	s_waitcnt vmcnt(4)
	v_lshlrev_b32_e32 v46, 16, v12
	v_and_b32_e32 v47, 0xffff0000, v12
	v_lshlrev_b32_e32 v48, 16, v13
	v_and_b32_e32 v49, 0xffff0000, v13
	v_lshlrev_b32_e32 v50, 16, v14
	v_and_b32_e32 v51, 0xffff0000, v14
	v_lshlrev_b32_e32 v52, 16, v15
	v_and_b32_e32 v53, 0xffff0000, v15
	v_mul_f32_e32 v54, 0xbfb8aa3b, v46
	v_mul_f32_e32 v55, 0xbfb8aa3b, v47
	v_mul_f32_e32 v56, 0xbfb8aa3b, v48
	v_mul_f32_e32 v57, 0xbfb8aa3b, v49
	v_mul_f32_e32 v58, 0xbfb8aa3b, v50
	v_mul_f32_e32 v59, 0xbfb8aa3b, v51
	v_mul_f32_e32 v60, 0xbfb8aa3b, v52
	v_mul_f32_e32 v61, 0xbfb8aa3b, v53
	v_exp_f32_e32 v54, v54
	v_exp_f32_e32 v55, v55
	v_exp_f32_e32 v56, v56
	v_exp_f32_e32 v57, v57
	v_exp_f32_e32 v58, v58
	v_exp_f32_e32 v59, v59
	v_exp_f32_e32 v60, v60
	v_exp_f32_e32 v61, v61
	v_lshlrev_b32_e32 v62, 16, v4
	v_and_b32_e32 v63, 0xffff0000, v4
	v_lshlrev_b32_e32 v78, 16, v8
	v_and_b32_e32 v79, 0xffff0000, v8
	v_lshlrev_b32_e32 v64, 16, v5
	v_and_b32_e32 v65, 0xffff0000, v5
	v_lshlrev_b32_e32 v80, 16, v9
	v_and_b32_e32 v81, 0xffff0000, v9
	v_lshlrev_b32_e32 v66, 16, v6
	v_and_b32_e32 v67, 0xffff0000, v6
	v_lshlrev_b32_e32 v82, 16, v10
	v_and_b32_e32 v83, 0xffff0000, v10
	v_lshlrev_b32_e32 v68, 16, v7
	v_and_b32_e32 v69, 0xffff0000, v7
	v_lshlrev_b32_e32 v84, 16, v11
	v_and_b32_e32 v85, 0xffff0000, v11
	v_add_f32_e32 v54, 1.0, v54
	v_add_f32_e32 v55, 1.0, v55
	v_add_f32_e32 v56, 1.0, v56
	v_add_f32_e32 v57, 1.0, v57
	v_add_f32_e32 v58, 1.0, v58
	v_add_f32_e32 v59, 1.0, v59
	v_add_f32_e32 v60, 1.0, v60
	v_add_f32_e32 v61, 1.0, v61
	v_rcp_f32_e32 v54, v54
	v_rcp_f32_e32 v55, v55
	v_rcp_f32_e32 v56, v56
	v_rcp_f32_e32 v57, v57
	v_rcp_f32_e32 v58, v58
	v_rcp_f32_e32 v59, v59
	v_rcp_f32_e32 v60, v60
	v_rcp_f32_e32 v61, v61
	v_lshlrev_b32_e32 v70, 16, v16
	v_and_b32_e32 v71, 0xffff0000, v16
	v_lshlrev_b32_e32 v72, 16, v17
	v_and_b32_e32 v73, 0xffff0000, v17
	v_lshlrev_b32_e32 v74, 16, v18
	v_and_b32_e32 v75, 0xffff0000, v18
	v_lshlrev_b32_e32 v76, 16, v19
	v_and_b32_e32 v77, 0xffff0000, v19
	v_pk_add_f32 v[62:63], v[62:63], v[78:79]
	v_pk_add_f32 v[64:65], v[64:65], v[80:81]
	v_pk_add_f32 v[66:67], v[66:67], v[82:83]
	v_pk_add_f32 v[68:69], v[68:69], v[84:85]
	v_pk_mul_f32 v[54:55], v[54:55], v[46:47]
	v_pk_mul_f32 v[56:57], v[56:57], v[48:49]
	v_pk_mul_f32 v[58:59], v[58:59], v[50:51]
	v_pk_mul_f32 v[60:61], v[60:61], v[52:53]
	v_pk_fma_f32 v[62:63], v[44:45], v[70:71], v[62:63] op_sel_hi:[0,1,1]
	v_pk_fma_f32 v[64:65], v[44:45], v[72:73], v[64:65] op_sel_hi:[0,1,1]
	v_pk_fma_f32 v[66:67], v[44:45], v[74:75], v[66:67] op_sel_hi:[0,1,1]
	v_pk_fma_f32 v[68:69], v[44:45], v[76:77], v[68:69] op_sel_hi:[0,1,1]
	v_pk_mul_f32 v[62:63], v[62:63], v[54:55]
	v_pk_mul_f32 v[64:65], v[64:65], v[56:57]
	v_pk_mul_f32 v[66:67], v[66:67], v[58:59]
	v_pk_mul_f32 v[68:69], v[68:69], v[60:61]
	v_pk_mul_f32 v[46:47], v[62:63], v[62:63]
	v_pk_mul_f32 v[48:49], v[66:67], v[66:67]
	v_pk_fma_f32 v[46:47], v[64:65], v[64:65], v[46:47]
	v_pk_fma_f32 v[48:49], v[68:69], v[68:69], v[48:49]
	v_pk_add_f32 v[46:47], v[46:47], v[48:49]
	s_nop 0
	v_add_f32_e32 v46, v46, v47
	s_nop 1
	v_add_f32_dpp v46, v46, v46 quad_perm:[1,0,3,2] row_mask:0xf bank_mask:0xf
	s_nop 1
	v_add_f32_dpp v46, v46, v46 quad_perm:[2,3,0,1] row_mask:0xf bank_mask:0xf
	s_nop 1
	v_add_f32_dpp v46, v46, v46 row_half_mirror row_mask:0xf bank_mask:0xf
	s_nop 1
	v_add_f32_dpp v46, v46, v46 row_mirror row_mask:0xf bank_mask:0xf
	s_nop 1
	ds_swizzle_b32 v47, v46 offset:swizzle(SWAP,16)
	s_waitcnt lgkmcnt(0)
	v_add_f32_e32 v46, v46, v47
	v_fmamk_f32 v46, v46, 0x3b800000, v174
	v_rsq_f32_e32 v46, v46
	s_nop 0
	v_pk_mul_f32 v[62:63], v[62:63], v[46:47] op_sel_hi:[1,0]
	v_pk_mul_f32 v[64:65], v[64:65], v[46:47] op_sel_hi:[1,0]
	v_pk_mul_f32 v[66:67], v[66:67], v[46:47] op_sel_hi:[1,0]
	v_pk_mul_f32 v[68:69], v[68:69], v[46:47] op_sel_hi:[1,0]
	v_pk_mul_f32 v[62:63], v[62:63], v[36:37]
	v_pk_mul_f32 v[64:65], v[64:65], v[38:39]
	v_pk_mul_f32 v[66:67], v[66:67], v[40:41]
	v_pk_mul_f32 v[68:69], v[68:69], v[42:43]
	v_cvt_pk_bf16_f32 v88, v62, v63
	v_cvt_pk_bf16_f32 v89, v64, v65
	v_cvt_pk_bf16_f32 v90, v66, v67
	v_cvt_pk_bf16_f32 v91, v68, v69
	global_load_dwordx4 v[4:7], v100, s[4:5] nt
	global_load_dwordx4 v[8:11], v100, s[6:7] nt
	global_load_dwordx4 v[12:15], v100, vcc
	global_load_dwordx4 v[16:19], v101, s[14:15]
	s_add_u32 s4, s4, s16
	s_addc_u32 s5, s5, 0
	s_add_u32 s6, s6, s16
	s_addc_u32 s7, s7, 0
	s_add_u32 vcc_lo, vcc_lo, s16
	s_addc_u32 vcc_hi, vcc_hi, 0
	s_add_u32 s14, s14, s17
	s_addc_u32 s15, s15, 0
	global_store_dwordx4 v100, v[88:91], s[8:9]
	s_add_u32 s8, s8, s16
	s_addc_u32 s9, s9, 0
	s_add_u32 s18, s18, s28
	s_cmp_lt_u32 s18, s35
	s_cbranch_scc0 .Lc_exit
	s_waitcnt vmcnt(5)
	v_lshlrev_b32_e32 v46, 16, v28
	v_and_b32_e32 v47, 0xffff0000, v28
	v_lshlrev_b32_e32 v48, 16, v29
	v_and_b32_e32 v49, 0xffff0000, v29
	v_lshlrev_b32_e32 v50, 16, v30
	v_and_b32_e32 v51, 0xffff0000, v30
	v_lshlrev_b32_e32 v52, 16, v31
	v_and_b32_e32 v53, 0xffff0000, v31
	v_mul_f32_e32 v54, 0xbfb8aa3b, v46
	v_mul_f32_e32 v55, 0xbfb8aa3b, v47
	v_mul_f32_e32 v56, 0xbfb8aa3b, v48
	v_mul_f32_e32 v57, 0xbfb8aa3b, v49
	v_mul_f32_e32 v58, 0xbfb8aa3b, v50
	v_mul_f32_e32 v59, 0xbfb8aa3b, v51
	v_mul_f32_e32 v60, 0xbfb8aa3b, v52
	v_mul_f32_e32 v61, 0xbfb8aa3b, v53
	v_exp_f32_e32 v54, v54
	v_exp_f32_e32 v55, v55
	v_exp_f32_e32 v56, v56
	v_exp_f32_e32 v57, v57
	v_exp_f32_e32 v58, v58
	v_exp_f32_e32 v59, v59
	v_exp_f32_e32 v60, v60
	v_exp_f32_e32 v61, v61
	v_lshlrev_b32_e32 v62, 16, v20
	v_and_b32_e32 v63, 0xffff0000, v20
	v_lshlrev_b32_e32 v78, 16, v24
	v_and_b32_e32 v79, 0xffff0000, v24
	v_lshlrev_b32_e32 v64, 16, v21
	v_and_b32_e32 v65, 0xffff0000, v21
	v_lshlrev_b32_e32 v80, 16, v25
	v_and_b32_e32 v81, 0xffff0000, v25
	v_lshlrev_b32_e32 v66, 16, v22
	v_and_b32_e32 v67, 0xffff0000, v22
	v_lshlrev_b32_e32 v82, 16, v26
	v_and_b32_e32 v83, 0xffff0000, v26
	v_lshlrev_b32_e32 v68, 16, v23
	v_and_b32_e32 v69, 0xffff0000, v23
	v_lshlrev_b32_e32 v84, 16, v27
	v_and_b32_e32 v85, 0xffff0000, v27
	v_add_f32_e32 v54, 1.0, v54
	v_add_f32_e32 v55, 1.0, v55
	v_add_f32_e32 v56, 1.0, v56
	v_add_f32_e32 v57, 1.0, v57
	v_add_f32_e32 v58, 1.0, v58
	v_add_f32_e32 v59, 1.0, v59
	v_add_f32_e32 v60, 1.0, v60
	v_add_f32_e32 v61, 1.0, v61
	v_rcp_f32_e32 v54, v54
	v_rcp_f32_e32 v55, v55
	v_rcp_f32_e32 v56, v56
	v_rcp_f32_e32 v57, v57
	v_rcp_f32_e32 v58, v58
	v_rcp_f32_e32 v59, v59
	v_rcp_f32_e32 v60, v60
	v_rcp_f32_e32 v61, v61
	v_lshlrev_b32_e32 v70, 16, v32
	v_and_b32_e32 v71, 0xffff0000, v32
	v_lshlrev_b32_e32 v72, 16, v33
	v_and_b32_e32 v73, 0xffff0000, v33
	v_lshlrev_b32_e32 v74, 16, v34
	v_and_b32_e32 v75, 0xffff0000, v34
	v_lshlrev_b32_e32 v76, 16, v35
	v_and_b32_e32 v77, 0xffff0000, v35
	v_pk_add_f32 v[62:63], v[62:63], v[78:79]
	v_pk_add_f32 v[64:65], v[64:65], v[80:81]
	v_pk_add_f32 v[66:67], v[66:67], v[82:83]
	v_pk_add_f32 v[68:69], v[68:69], v[84:85]
	v_pk_mul_f32 v[54:55], v[54:55], v[46:47]
	v_pk_mul_f32 v[56:57], v[56:57], v[48:49]
	v_pk_mul_f32 v[58:59], v[58:59], v[50:51]
	v_pk_mul_f32 v[60:61], v[60:61], v[52:53]
	v_pk_fma_f32 v[62:63], v[44:45], v[70:71], v[62:63] op_sel_hi:[0,1,1]
	v_pk_fma_f32 v[64:65], v[44:45], v[72:73], v[64:65] op_sel_hi:[0,1,1]
	v_pk_fma_f32 v[66:67], v[44:45], v[74:75], v[66:67] op_sel_hi:[0,1,1]
	v_pk_fma_f32 v[68:69], v[44:45], v[76:77], v[68:69] op_sel_hi:[0,1,1]
	v_pk_mul_f32 v[62:63], v[62:63], v[54:55]
	v_pk_mul_f32 v[64:65], v[64:65], v[56:57]
	v_pk_mul_f32 v[66:67], v[66:67], v[58:59]
	v_pk_mul_f32 v[68:69], v[68:69], v[60:61]
	v_pk_mul_f32 v[46:47], v[62:63], v[62:63]
	v_pk_mul_f32 v[48:49], v[66:67], v[66:67]
	v_pk_fma_f32 v[46:47], v[64:65], v[64:65], v[46:47]
	v_pk_fma_f32 v[48:49], v[68:69], v[68:69], v[48:49]
	v_pk_add_f32 v[46:47], v[46:47], v[48:49]
	s_nop 0
	v_add_f32_e32 v46, v46, v47
	s_nop 1
	v_add_f32_dpp v46, v46, v46 quad_perm:[1,0,3,2] row_mask:0xf bank_mask:0xf
	s_nop 1
	v_add_f32_dpp v46, v46, v46 quad_perm:[2,3,0,1] row_mask:0xf bank_mask:0xf
	s_nop 1
	v_add_f32_dpp v46, v46, v46 row_half_mirror row_mask:0xf bank_mask:0xf
	s_nop 1
	v_add_f32_dpp v46, v46, v46 row_mirror row_mask:0xf bank_mask:0xf
	s_nop 1
	ds_swizzle_b32 v47, v46 offset:swizzle(SWAP,16)
	s_waitcnt lgkmcnt(0)
	v_add_f32_e32 v46, v46, v47
	v_fmamk_f32 v46, v46, 0x3b800000, v174
	v_rsq_f32_e32 v46, v46
	s_nop 0
	v_pk_mul_f32 v[62:63], v[62:63], v[46:47] op_sel_hi:[1,0]
	v_pk_mul_f32 v[64:65], v[64:65], v[46:47] op_sel_hi:[1,0]
	v_pk_mul_f32 v[66:67], v[66:67], v[46:47] op_sel_hi:[1,0]
	v_pk_mul_f32 v[68:69], v[68:69], v[46:47] op_sel_hi:[1,0]
	v_pk_mul_f32 v[62:63], v[62:63], v[36:37]
	v_pk_mul_f32 v[64:65], v[64:65], v[38:39]
	v_pk_mul_f32 v[66:67], v[66:67], v[40:41]
	v_pk_mul_f32 v[68:69], v[68:69], v[42:43]
	v_cvt_pk_bf16_f32 v88, v62, v63
	v_cvt_pk_bf16_f32 v89, v64, v65
	v_cvt_pk_bf16_f32 v90, v66, v67
	v_cvt_pk_bf16_f32 v91, v68, v69
	global_load_dwordx4 v[20:23], v100, s[4:5] nt
	global_load_dwordx4 v[24:27], v100, s[6:7] nt
	global_load_dwordx4 v[28:31], v100, vcc
	global_load_dwordx4 v[32:35], v101, s[14:15]
	s_add_u32 s4, s4, s16
	s_addc_u32 s5, s5, 0
	s_add_u32 s6, s6, s16
	s_addc_u32 s7, s7, 0
	s_add_u32 vcc_lo, vcc_lo, s16
	s_addc_u32 vcc_hi, vcc_hi, 0
	s_add_u32 s14, s14, s17
	s_addc_u32 s15, s15, 0
	global_store_dwordx4 v100, v[88:91], s[8:9]
	s_add_u32 s8, s8, s16
	s_addc_u32 s9, s9, 0
	s_add_u32 s18, s18, s28
	s_cmp_lt_u32 s18, s35
	s_cbranch_scc0 .Lc_exit
.Lc_loop:
	s_waitcnt vmcnt(6)
	v_lshlrev_b32_e32 v46, 16, v12
	v_and_b32_e32 v47, 0xffff0000, v12
	v_lshlrev_b32_e32 v48, 16, v13
	v_and_b32_e32 v49, 0xffff0000, v13
	v_lshlrev_b32_e32 v50, 16, v14
	v_and_b32_e32 v51, 0xffff0000, v14
	v_lshlrev_b32_e32 v52, 16, v15
	v_and_b32_e32 v53, 0xffff0000, v15
	v_mul_f32_e32 v54, 0xbfb8aa3b, v46
	v_mul_f32_e32 v55, 0xbfb8aa3b, v47
	v_mul_f32_e32 v56, 0xbfb8aa3b, v48
	v_mul_f32_e32 v57, 0xbfb8aa3b, v49
	v_mul_f32_e32 v58, 0xbfb8aa3b, v50
	v_mul_f32_e32 v59, 0xbfb8aa3b, v51
	v_mul_f32_e32 v60, 0xbfb8aa3b, v52
	v_mul_f32_e32 v61, 0xbfb8aa3b, v53
	v_exp_f32_e32 v54, v54
	v_exp_f32_e32 v55, v55
	v_exp_f32_e32 v56, v56
	v_exp_f32_e32 v57, v57
	v_exp_f32_e32 v58, v58
	v_exp_f32_e32 v59, v59
	v_exp_f32_e32 v60, v60
	v_exp_f32_e32 v61, v61
	v_lshlrev_b32_e32 v62, 16, v4
	v_and_b32_e32 v63, 0xffff0000, v4
	v_lshlrev_b32_e32 v78, 16, v8
	v_and_b32_e32 v79, 0xffff0000, v8
	v_lshlrev_b32_e32 v64, 16, v5
	v_and_b32_e32 v65, 0xffff0000, v5
	v_lshlrev_b32_e32 v80, 16, v9
	v_and_b32_e32 v81, 0xffff0000, v9
	v_lshlrev_b32_e32 v66, 16, v6
	v_and_b32_e32 v67, 0xffff0000, v6
	v_lshlrev_b32_e32 v82, 16, v10
	v_and_b32_e32 v83, 0xffff0000, v10
	v_lshlrev_b32_e32 v68, 16, v7
	v_and_b32_e32 v69, 0xffff0000, v7
	v_lshlrev_b32_e32 v84, 16, v11
	v_and_b32_e32 v85, 0xffff0000, v11
	v_add_f32_e32 v54, 1.0, v54
	v_add_f32_e32 v55, 1.0, v55
	v_add_f32_e32 v56, 1.0, v56
	v_add_f32_e32 v57, 1.0, v57
	v_add_f32_e32 v58, 1.0, v58
	v_add_f32_e32 v59, 1.0, v59
	v_add_f32_e32 v60, 1.0, v60
	v_add_f32_e32 v61, 1.0, v61
	v_rcp_f32_e32 v54, v54
	v_rcp_f32_e32 v55, v55
	v_rcp_f32_e32 v56, v56
	v_rcp_f32_e32 v57, v57
	v_rcp_f32_e32 v58, v58
	v_rcp_f32_e32 v59, v59
	v_rcp_f32_e32 v60, v60
	v_rcp_f32_e32 v61, v61
	v_lshlrev_b32_e32 v70, 16, v16
	v_and_b32_e32 v71, 0xffff0000, v16
	v_lshlrev_b32_e32 v72, 16, v17
	v_and_b32_e32 v73, 0xffff0000, v17
	v_lshlrev_b32_e32 v74, 16, v18
	v_and_b32_e32 v75, 0xffff0000, v18
	v_lshlrev_b32_e32 v76, 16, v19
	v_and_b32_e32 v77, 0xffff0000, v19
	v_pk_add_f32 v[62:63], v[62:63], v[78:79]
	v_pk_add_f32 v[64:65], v[64:65], v[80:81]
	v_pk_add_f32 v[66:67], v[66:67], v[82:83]
	v_pk_add_f32 v[68:69], v[68:69], v[84:85]
	v_pk_mul_f32 v[54:55], v[54:55], v[46:47]
	v_pk_mul_f32 v[56:57], v[56:57], v[48:49]
	v_pk_mul_f32 v[58:59], v[58:59], v[50:51]
	v_pk_mul_f32 v[60:61], v[60:61], v[52:53]
	v_pk_fma_f32 v[62:63], v[44:45], v[70:71], v[62:63] op_sel_hi:[0,1,1]
	v_pk_fma_f32 v[64:65], v[44:45], v[72:73], v[64:65] op_sel_hi:[0,1,1]
	v_pk_fma_f32 v[66:67], v[44:45], v[74:75], v[66:67] op_sel_hi:[0,1,1]
	v_pk_fma_f32 v[68:69], v[44:45], v[76:77], v[68:69] op_sel_hi:[0,1,1]
	v_pk_mul_f32 v[62:63], v[62:63], v[54:55]
	v_pk_mul_f32 v[64:65], v[64:65], v[56:57]
	v_pk_mul_f32 v[66:67], v[66:67], v[58:59]
	v_pk_mul_f32 v[68:69], v[68:69], v[60:61]
	v_pk_mul_f32 v[46:47], v[62:63], v[62:63]
	v_pk_mul_f32 v[48:49], v[66:67], v[66:67]
	v_pk_fma_f32 v[46:47], v[64:65], v[64:65], v[46:47]
	v_pk_fma_f32 v[48:49], v[68:69], v[68:69], v[48:49]
	v_pk_add_f32 v[46:47], v[46:47], v[48:49]
	s_nop 0
	v_add_f32_e32 v46, v46, v47
	s_nop 1
	v_add_f32_dpp v46, v46, v46 quad_perm:[1,0,3,2] row_mask:0xf bank_mask:0xf
	s_nop 1
	v_add_f32_dpp v46, v46, v46 quad_perm:[2,3,0,1] row_mask:0xf bank_mask:0xf
	s_nop 1
	v_add_f32_dpp v46, v46, v46 row_half_mirror row_mask:0xf bank_mask:0xf
	s_nop 1
	v_add_f32_dpp v46, v46, v46 row_mirror row_mask:0xf bank_mask:0xf
	s_nop 1
	ds_swizzle_b32 v47, v46 offset:swizzle(SWAP,16)
	s_waitcnt lgkmcnt(0)
	v_add_f32_e32 v46, v46, v47
	v_fmamk_f32 v46, v46, 0x3b800000, v174
	v_rsq_f32_e32 v46, v46
	s_nop 0
	v_pk_mul_f32 v[62:63], v[62:63], v[46:47] op_sel_hi:[1,0]
	v_pk_mul_f32 v[64:65], v[64:65], v[46:47] op_sel_hi:[1,0]
	v_pk_mul_f32 v[66:67], v[66:67], v[46:47] op_sel_hi:[1,0]
	v_pk_mul_f32 v[68:69], v[68:69], v[46:47] op_sel_hi:[1,0]
	v_pk_mul_f32 v[62:63], v[62:63], v[36:37]
	v_pk_mul_f32 v[64:65], v[64:65], v[38:39]
	v_pk_mul_f32 v[66:67], v[66:67], v[40:41]
	v_pk_mul_f32 v[68:69], v[68:69], v[42:43]
	v_cvt_pk_bf16_f32 v88, v62, v63
	v_cvt_pk_bf16_f32 v89, v64, v65
	v_cvt_pk_bf16_f32 v90, v66, v67
	v_cvt_pk_bf16_f32 v91, v68, v69
	global_load_dwordx4 v[4:7], v100, s[4:5] nt
	global_load_dwordx4 v[8:11], v100, s[6:7] nt
	global_load_dwordx4 v[12:15], v100, vcc
	global_load_dwordx4 v[16:19], v101, s[14:15]
	s_add_u32 s4, s4, s16
	s_addc_u32 s5, s5, 0
	s_add_u32 s6, s6, s16
	s_addc_u32 s7, s7, 0
	s_add_u32 vcc_lo, vcc_lo, s16
	s_addc_u32 vcc_hi, vcc_hi, 0
	s_add_u32 s14, s14, s17
	s_addc_u32 s15, s15, 0
	global_store_dwordx4 v100, v[88:91], s[8:9]
	s_add_u32 s8, s8, s16
	s_addc_u32 s9, s9, 0
	s_add_u32 s18, s18, s28
	s_cmp_lt_u32 s18, s35
	s_cbranch_scc0 .Lc_exit
	s_waitcnt vmcnt(6)
	v_lshlrev_b32_e32 v46, 16, v28
	v_and_b32_e32 v47, 0xffff0000, v28
	v_lshlrev_b32_e32 v48, 16, v29
	v_and_b32_e32 v49, 0xffff0000, v29
	v_lshlrev_b32_e32 v50, 16, v30
	v_and_b32_e32 v51, 0xffff0000, v30
	v_lshlrev_b32_e32 v52, 16, v31
	v_and_b32_e32 v53, 0xffff0000, v31
	v_mul_f32_e32 v54, 0xbfb8aa3b, v46
	v_mul_f32_e32 v55, 0xbfb8aa3b, v47
	v_mul_f32_e32 v56, 0xbfb8aa3b, v48
	v_mul_f32_e32 v57, 0xbfb8aa3b, v49
	v_mul_f32_e32 v58, 0xbfb8aa3b, v50
	v_mul_f32_e32 v59, 0xbfb8aa3b, v51
	v_mul_f32_e32 v60, 0xbfb8aa3b, v52
	v_mul_f32_e32 v61, 0xbfb8aa3b, v53
	v_exp_f32_e32 v54, v54
	v_exp_f32_e32 v55, v55
	v_exp_f32_e32 v56, v56
	v_exp_f32_e32 v57, v57
	v_exp_f32_e32 v58, v58
	v_exp_f32_e32 v59, v59
	v_exp_f32_e32 v60, v60
	v_exp_f32_e32 v61, v61
	v_lshlrev_b32_e32 v62, 16, v20
	v_and_b32_e32 v63, 0xffff0000, v20
	v_lshlrev_b32_e32 v78, 16, v24
	v_and_b32_e32 v79, 0xffff0000, v24
	v_lshlrev_b32_e32 v64, 16, v21
	v_and_b32_e32 v65, 0xffff0000, v21
	v_lshlrev_b32_e32 v80, 16, v25
	v_and_b32_e32 v81, 0xffff0000, v25
	v_lshlrev_b32_e32 v66, 16, v22
	v_and_b32_e32 v67, 0xffff0000, v22
	v_lshlrev_b32_e32 v82, 16, v26
	v_and_b32_e32 v83, 0xffff0000, v26
	v_lshlrev_b32_e32 v68, 16, v23
	v_and_b32_e32 v69, 0xffff0000, v23
	v_lshlrev_b32_e32 v84, 16, v27
	v_and_b32_e32 v85, 0xffff0000, v27
	v_add_f32_e32 v54, 1.0, v54
	v_add_f32_e32 v55, 1.0, v55
	v_add_f32_e32 v56, 1.0, v56
	v_add_f32_e32 v57, 1.0, v57
	v_add_f32_e32 v58, 1.0, v58
	v_add_f32_e32 v59, 1.0, v59
	v_add_f32_e32 v60, 1.0, v60
	v_add_f32_e32 v61, 1.0, v61
	v_rcp_f32_e32 v54, v54
	v_rcp_f32_e32 v55, v55
	v_rcp_f32_e32 v56, v56
	v_rcp_f32_e32 v57, v57
	v_rcp_f32_e32 v58, v58
	v_rcp_f32_e32 v59, v59
	v_rcp_f32_e32 v60, v60
	v_rcp_f32_e32 v61, v61
	v_lshlrev_b32_e32 v70, 16, v32
	v_and_b32_e32 v71, 0xffff0000, v32
	v_lshlrev_b32_e32 v72, 16, v33
	v_and_b32_e32 v73, 0xffff0000, v33
	v_lshlrev_b32_e32 v74, 16, v34
	v_and_b32_e32 v75, 0xffff0000, v34
	v_lshlrev_b32_e32 v76, 16, v35
	v_and_b32_e32 v77, 0xffff0000, v35
	v_pk_add_f32 v[62:63], v[62:63], v[78:79]
	v_pk_add_f32 v[64:65], v[64:65], v[80:81]
	v_pk_add_f32 v[66:67], v[66:67], v[82:83]
	v_pk_add_f32 v[68:69], v[68:69], v[84:85]
	v_pk_mul_f32 v[54:55], v[54:55], v[46:47]
	v_pk_mul_f32 v[56:57], v[56:57], v[48:49]
	v_pk_mul_f32 v[58:59], v[58:59], v[50:51]
	v_pk_mul_f32 v[60:61], v[60:61], v[52:53]
	v_pk_fma_f32 v[62:63], v[44:45], v[70:71], v[62:63] op_sel_hi:[0,1,1]
	v_pk_fma_f32 v[64:65], v[44:45], v[72:73], v[64:65] op_sel_hi:[0,1,1]
	v_pk_fma_f32 v[66:67], v[44:45], v[74:75], v[66:67] op_sel_hi:[0,1,1]
	v_pk_fma_f32 v[68:69], v[44:45], v[76:77], v[68:69] op_sel_hi:[0,1,1]
	v_pk_mul_f32 v[62:63], v[62:63], v[54:55]
	v_pk_mul_f32 v[64:65], v[64:65], v[56:57]
	v_pk_mul_f32 v[66:67], v[66:67], v[58:59]
	v_pk_mul_f32 v[68:69], v[68:69], v[60:61]
	v_pk_mul_f32 v[46:47], v[62:63], v[62:63]
	v_pk_mul_f32 v[48:49], v[66:67], v[66:67]
	v_pk_fma_f32 v[46:47], v[64:65], v[64:65], v[46:47]
	v_pk_fma_f32 v[48:49], v[68:69], v[68:69], v[48:49]
	v_pk_add_f32 v[46:47], v[46:47], v[48:49]
	s_nop 0
	v_add_f32_e32 v46, v46, v47
	s_nop 1
	v_add_f32_dpp v46, v46, v46 quad_perm:[1,0,3,2] row_mask:0xf bank_mask:0xf
	s_nop 1
	v_add_f32_dpp v46, v46, v46 quad_perm:[2,3,0,1] row_mask:0xf bank_mask:0xf
	s_nop 1
	v_add_f32_dpp v46, v46, v46 row_half_mirror row_mask:0xf bank_mask:0xf
	s_nop 1
	v_add_f32_dpp v46, v46, v46 row_mirror row_mask:0xf bank_mask:0xf
	s_nop 1
	ds_swizzle_b32 v47, v46 offset:swizzle(SWAP,16)
	s_waitcnt lgkmcnt(0)
	v_add_f32_e32 v46, v46, v47
	v_fmamk_f32 v46, v46, 0x3b800000, v174
	v_rsq_f32_e32 v46, v46
	s_nop 0
	v_pk_mul_f32 v[62:63], v[62:63], v[46:47] op_sel_hi:[1,0]
	v_pk_mul_f32 v[64:65], v[64:65], v[46:47] op_sel_hi:[1,0]
	v_pk_mul_f32 v[66:67], v[66:67], v[46:47] op_sel_hi:[1,0]
	v_pk_mul_f32 v[68:69], v[68:69], v[46:47] op_sel_hi:[1,0]
	v_pk_mul_f32 v[62:63], v[62:63], v[36:37]
	v_pk_mul_f32 v[64:65], v[64:65], v[38:39]
	v_pk_mul_f32 v[66:67], v[66:67], v[40:41]
	v_pk_mul_f32 v[68:69], v[68:69], v[42:43]
	v_cvt_pk_bf16_f32 v88, v62, v63
	v_cvt_pk_bf16_f32 v89, v64, v65
	v_cvt_pk_bf16_f32 v90, v66, v67
	v_cvt_pk_bf16_f32 v91, v68, v69
	global_load_dwordx4 v[20:23], v100, s[4:5] nt
	global_load_dwordx4 v[24:27], v100, s[6:7] nt
	global_load_dwordx4 v[28:31], v100, vcc
	global_load_dwordx4 v[32:35], v101, s[14:15]
	s_add_u32 s4, s4, s16
	s_addc_u32 s5, s5, 0
	s_add_u32 s6, s6, s16
	s_addc_u32 s7, s7, 0
	s_add_u32 vcc_lo, vcc_lo, s16
	s_addc_u32 vcc_hi, vcc_hi, 0
	s_add_u32 s14, s14, s17
	s_addc_u32 s15, s15, 0
	global_store_dwordx4 v100, v[88:91], s[8:9]
	s_add_u32 s8, s8, s16
	s_addc_u32 s9, s9, 0
	s_add_u32 s18, s18, s28
	s_cmp_lt_u32 s18, s35
	s_cbranch_scc0 .Lc_exit
	s_branch .Lc_loop
.Lc_exit:
	s_waitcnt vmcnt(0)
	s_mov_b64 s[4:5], 0

.LBB0_245:
	s_andn2_b64 vcc, exec, s[4:5]
	s_cbranch_vccnz .LBB0_310
	v_readlane_b32 s4, v253, 14
	v_mov_b32_e32 v1, v175
	v_readlane_b32 s5, v253, 15
	s_andn2_b64 vcc, exec, s[4:5]
	v_readfirstlane_b32 s3, v1
	s_cbranch_vccnz .LBB0_310
	v_writelane_b32 v255, s96, 7
	v_writelane_b32 v255, s97, 8
	v_writelane_b32 v255, s98, 9
	v_writelane_b32 v255, s99, 10
	v_writelane_b32 v255, s86, 0
	v_writelane_b32 v255, s87, 1
	v_writelane_b32 v255, s42, 11
	v_writelane_b32 v255, s43, 12
	v_lshrrev_b32_e32 v1, 6, v175
	s_lshl_b32 s4, s42, 8
	v_readfirstlane_b32 s3, v1
	s_add_u32 s56, s94, s4
	s_addc_u32 s57, s95, 0
	v_readlane_b32 s58, v253, 3
	v_readlane_b32 s61, v253, 5
	s_movk_i32 s59, 0x110
	s_movk_i32 s60, 0x40
	s_nop 3

.Lm_w456_13:
	s_cmp_lt_u32 s3, 7
	s_cbranch_scc0 .Lm_g0_8
	ds_read_b128 v[116:119], v216 offset:0
	ds_read_b128 v[120:123], v217 offset:34816
	ds_read_b128 v[128:131], v216 offset:32
	ds_read_b128 v[132:135], v217 offset:34848
	ds_read_b128 v[140:143], v216 offset:64
	ds_read_b128 v[144:147], v217 offset:34880
	ds_read_b128 v[152:155], v216 offset:96
	ds_read_b128 v[156:159], v217 offset:34912
	s_waitcnt lgkmcnt(6)
	v_mfma_f32_32x32x16_bf16 v[76:91], v[116:119], v[120:123], 0
	ds_read_b128 v[116:119], v216 offset:128
	ds_read_b128 v[120:123], v217 offset:34944
	global_load_dwordx4 v[4:7], v164, s[38:39]
	s_waitcnt lgkmcnt(6)
	v_mfma_f32_32x32x16_bf16 v[76:91], v[128:131], v[132:135], v[76:91]
	ds_read_b128 v[128:131], v216 offset:160
	ds_read_b128 v[132:135], v217 offset:34976
	global_load_dwordx4 v[20:23], v164, s[38:39] offset:256
	s_waitcnt lgkmcnt(6)
	v_mfma_f32_32x32x16_bf16 v[76:91], v[140:143], v[144:147], v[76:91]
	ds_read_b128 v[140:143], v216 offset:192
	ds_read_b128 v[144:147], v217 offset:35008
	global_load_dwordx4 v[8:11], v165, s[38:39]
	s_waitcnt lgkmcnt(6)
	v_mfma_f32_32x32x16_bf16 v[76:91], v[152:155], v[156:159], v[76:91]
	ds_read_b128 v[152:155], v216 offset:224
	ds_read_b128 v[156:159], v217 offset:35040
	global_load_dwordx4 v[24:27], v165, s[38:39] offset:256
	s_waitcnt lgkmcnt(6)
	v_mfma_f32_32x32x16_bf16 v[76:91], v[116:119], v[120:123], v[76:91]
	global_load_dwordx4 v[12:15], v166, s[38:39]
	ds_read_b128 v[234:237], v222 offset:0
	ds_read_b128 v[238:241], v222 offset:32
	ds_read_b128 v[242:245], v222 offset:64
	ds_read_b128 v[246:249], v222 offset:96
	ds_read_b32 v250, v223 offset:0
	s_waitcnt lgkmcnt(9)
	v_mfma_f32_32x32x16_bf16 v[76:91], v[128:131], v[132:135], v[76:91]
	global_load_dwordx4 v[28:31], v166, s[38:39] offset:256
	s_waitcnt lgkmcnt(7)
	v_mfma_f32_32x32x16_bf16 v[76:91], v[140:143], v[144:147], v[76:91]
	global_load_dwordx4 v[16:19], v167, s[38:39]
	s_waitcnt lgkmcnt(5)
	v_mfma_f32_32x32x16_bf16 v[76:91], v[152:155], v[156:159], v[76:91]
	global_load_dwordx4 v[32:35], v167, s[38:39] offset:256
	global_load_dwordx4 v[36:39], v168, s[40:41]
	s_add_u32 s38, s38, s46
	s_addc_u32 s39, s39, s55
	s_add_u32 s40, s40, s47
	s_addc_u32 s41, s41, s55
	s_waitcnt lgkmcnt(0)
	ds_read_b32 v1, v172 offset:0
	ds_read_b64_tr_b16 v[116:117], v193 offset:0
	ds_read_b64_tr_b16 v[118:119], v193 offset:1088
	ds_read_b64_tr_b16 v[120:121], v192 offset:0
	ds_read_b64_tr_b16 v[122:123], v192 offset:256
	ds_read_b64_tr_b16 v[124:125], v193 offset:4352
	ds_read_b64_tr_b16 v[126:127], v193 offset:5440
	ds_read_b64_tr_b16 v[128:129], v192 offset:1024
	ds_read_b64_tr_b16 v[130:131], v192 offset:1280
	ds_read_b64_tr_b16 v[132:133], v193 offset:8704
	ds_read_b64_tr_b16 v[134:135], v193 offset:9792
	ds_read_b64_tr_b16 v[136:137], v192 offset:2048
	ds_read_b64_tr_b16 v[138:139], v192 offset:2304
	s_waitcnt lgkmcnt(12)
	v_exp_f32_e32 v1, v1
	s_nop 0
	v_mul_f32_e32 v176, v176, v1
	v_mul_f32_e32 v177, v177, v1
	v_mul_f32_e32 v178, v178, v1
	v_mul_f32_e32 v179, v179, v1
	v_mul_f32_e32 v180, v180, v1
	v_mul_f32_e32 v181, v181, v1
	v_mul_f32_e32 v182, v182, v1
	v_mul_f32_e32 v183, v183, v1
	v_mul_f32_e32 v184, v184, v1
	v_mul_f32_e32 v185, v185, v1
	v_mul_f32_e32 v186, v186, v1
	v_mul_f32_e32 v187, v187, v1
	v_mul_f32_e32 v188, v188, v1
	v_mul_f32_e32 v189, v189, v1
	v_mul_f32_e32 v190, v190, v1
	v_mul_f32_e32 v191, v191, v1
	s_nop 1
	s_cmp_eq_u32 s53, 0
	s_cbranch_scc0 .Lm_sdiag_19
	s_waitcnt lgkmcnt(8)
	v_mfma_f32_32x32x16_bf16 v[176:191], v[116:119], v[120:123], v[176:191]
	ds_read_b64_tr_b16 v[116:117], v193 offset:13056
	ds_read_b64_tr_b16 v[118:119], v193 offset:14144
	ds_read_b64_tr_b16 v[120:121], v192 offset:3072
	ds_read_b64_tr_b16 v[122:123], v192 offset:3328
	v_sub_f32_e32 v140, v234, v250
	v_sub_f32_e32 v141, v235, v250
	v_sub_f32_e32 v142, v236, v250
	v_sub_f32_e32 v143, v237, v250
	v_sub_f32_e32 v144, v238, v250
	v_sub_f32_e32 v145, v239, v250
	v_sub_f32_e32 v146, v240, v250
	s_waitcnt lgkmcnt(8)
	v_mfma_f32_32x32x16_bf16 v[176:191], v[124:127], v[128:131], v[176:191]
	ds_read_b64_tr_b16 v[124:125], v193 offset:17408
	ds_read_b64_tr_b16 v[126:127], v193 offset:18496
	ds_read_b64_tr_b16 v[128:129], v192 offset:4096
	ds_read_b64_tr_b16 v[130:131], v192 offset:4352
	v_sub_f32_e32 v147, v241, v250
	v_sub_f32_e32 v148, v242, v250
	v_sub_f32_e32 v149, v243, v250
	v_sub_f32_e32 v150, v244, v250
	v_sub_f32_e32 v151, v245, v250
	v_sub_f32_e32 v152, v246, v250
	v_sub_f32_e32 v153, v247, v250
	s_waitcnt lgkmcnt(8)
	v_mfma_f32_32x32x16_bf16 v[176:191], v[132:135], v[136:139], v[176:191]
	ds_read_b64_tr_b16 v[132:133], v193 offset:21760
	ds_read_b64_tr_b16 v[134:135], v193 offset:22848
	ds_read_b64_tr_b16 v[136:137], v192 offset:5120
	ds_read_b64_tr_b16 v[138:139], v192 offset:5376
	v_sub_f32_e32 v154, v248, v250
	v_sub_f32_e32 v155, v249, v250
	v_exp_f32_e32 v140, v140
	v_exp_f32_e32 v141, v141
	v_exp_f32_e32 v142, v142
	v_exp_f32_e32 v143, v143
	v_exp_f32_e32 v144, v144
	s_waitcnt lgkmcnt(8)
	v_mfma_f32_32x32x16_bf16 v[176:191], v[116:119], v[120:123], v[176:191]
	ds_read_b64_tr_b16 v[116:117], v193 offset:26112
	ds_read_b64_tr_b16 v[118:119], v193 offset:27200
	ds_read_b64_tr_b16 v[120:121], v192 offset:6144
	ds_read_b64_tr_b16 v[122:123], v192 offset:6400
	v_exp_f32_e32 v145, v145
	v_exp_f32_e32 v146, v146
	v_exp_f32_e32 v147, v147
	v_exp_f32_e32 v148, v148
	v_exp_f32_e32 v149, v149
	v_exp_f32_e32 v150, v150
	v_exp_f32_e32 v151, v151
	s_waitcnt lgkmcnt(8)
	v_mfma_f32_32x32x16_bf16 v[176:191], v[124:127], v[128:131], v[176:191]
	ds_read_b64_tr_b16 v[124:125], v193 offset:30464
	ds_read_b64_tr_b16 v[126:127], v193 offset:31552
	ds_read_b64_tr_b16 v[128:129], v192 offset:7168
	ds_read_b64_tr_b16 v[130:131], v192 offset:7424
	v_exp_f32_e32 v152, v152
	v_exp_f32_e32 v153, v153
	v_exp_f32_e32 v154, v154
	v_exp_f32_e32 v155, v155
	v_mul_f32_e32 v76, v76, v140
	v_mul_f32_e32 v77, v77, v141
	v_mul_f32_e32 v78, v78, v142
	s_waitcnt lgkmcnt(8)
	v_mfma_f32_32x32x16_bf16 v[176:191], v[132:135], v[136:139], v[176:191]
	v_mul_f32_e32 v79, v79, v143
	v_mul_f32_e32 v80, v80, v144
	v_mul_f32_e32 v81, v81, v145
	v_mul_f32_e32 v82, v82, v146
	v_mul_f32_e32 v83, v83, v147
	v_mul_f32_e32 v84, v84, v148
	v_mul_f32_e32 v85, v85, v149
	s_waitcnt lgkmcnt(4)
	v_mfma_f32_32x32x16_bf16 v[176:191], v[116:119], v[120:123], v[176:191]
	v_mul_f32_e32 v86, v86, v150
	v_mul_f32_e32 v87, v87, v151
	v_mul_f32_e32 v88, v88, v152
	v_mul_f32_e32 v89, v89, v153
	v_mul_f32_e32 v90, v90, v154
	v_mul_f32_e32 v91, v91, v155
	v_cvt_pk_bf16_f32 v156, v76, v77
	s_waitcnt lgkmcnt(0)
	v_mfma_f32_32x32x16_bf16 v[176:191], v[124:127], v[128:131], v[176:191]
	v_cvt_pk_bf16_f32 v157, v78, v79
	v_cvt_pk_bf16_f32 v158, v80, v81
	v_cvt_pk_bf16_f32 v159, v82, v83
	v_cvt_pk_bf16_f32 v160, v84, v85
	v_cvt_pk_bf16_f32 v161, v86, v87
	v_cvt_pk_bf16_f32 v162, v88, v89
	v_cvt_pk_bf16_f32 v163, v90, v91
	s_branch .Lm_sjoin_20
.Lm_sdiag_19:
	s_waitcnt lgkmcnt(8)
	v_mfma_f32_32x32x16_bf16 v[176:191], v[116:119], v[120:123], v[176:191]
	ds_read_b64_tr_b16 v[116:117], v193 offset:13056
	ds_read_b64_tr_b16 v[118:119], v193 offset:14144
	ds_read_b64_tr_b16 v[120:121], v192 offset:3072
	ds_read_b64_tr_b16 v[122:123], v192 offset:3328
	v_sub_f32_e32 v140, v234, v250
	v_sub_f32_e32 v141, v235, v250
	v_sub_f32_e32 v142, v236, v250
	v_sub_f32_e32 v143, v237, v250
	v_sub_f32_e32 v144, v238, v250
	v_sub_f32_e32 v145, v239, v250
	v_sub_f32_e32 v146, v240, v250
	v_sub_f32_e32 v147, v241, v250
	v_sub_f32_e32 v148, v242, v250
	s_waitcnt lgkmcnt(8)
	v_mfma_f32_32x32x16_bf16 v[176:191], v[124:127], v[128:131], v[176:191]
	ds_read_b64_tr_b16 v[124:125], v193 offset:17408
	ds_read_b64_tr_b16 v[126:127], v193 offset:18496
	ds_read_b64_tr_b16 v[128:129], v192 offset:4096
	ds_read_b64_tr_b16 v[130:131], v192 offset:4352
	v_sub_f32_e32 v149, v243, v250
	v_sub_f32_e32 v150, v244, v250
	v_sub_f32_e32 v151, v245, v250
	v_sub_f32_e32 v152, v246, v250
	v_sub_f32_e32 v153, v247, v250
	v_sub_f32_e32 v154, v248, v250
	v_sub_f32_e32 v155, v249, v250
	v_exp_f32_e32 v140, v140
	v_exp_f32_e32 v141, v141
	s_waitcnt lgkmcnt(8)
	v_mfma_f32_32x32x16_bf16 v[176:191], v[132:135], v[136:139], v[176:191]
	ds_read_b64_tr_b16 v[132:133], v193 offset:21760
	ds_read_b64_tr_b16 v[134:135], v193 offset:22848
	ds_read_b64_tr_b16 v[136:137], v192 offset:5120
	ds_read_b64_tr_b16 v[138:139], v192 offset:5376
	v_exp_f32_e32 v142, v142
	v_exp_f32_e32 v143, v143
	v_exp_f32_e32 v144, v144
	v_exp_f32_e32 v145, v145
	v_exp_f32_e32 v146, v146
	v_exp_f32_e32 v147, v147
	v_exp_f32_e32 v148, v148
	v_exp_f32_e32 v149, v149
	v_exp_f32_e32 v150, v150
	s_waitcnt lgkmcnt(8)
	v_mfma_f32_32x32x16_bf16 v[176:191], v[116:119], v[120:123], v[176:191]
	ds_read_b64_tr_b16 v[116:117], v193 offset:26112
	ds_read_b64_tr_b16 v[118:119], v193 offset:27200
	ds_read_b64_tr_b16 v[120:121], v192 offset:6144
	ds_read_b64_tr_b16 v[122:123], v192 offset:6400
	v_exp_f32_e32 v151, v151
	v_exp_f32_e32 v152, v152
	v_exp_f32_e32 v153, v153
	v_exp_f32_e32 v154, v154
	v_exp_f32_e32 v155, v155
	v_mul_f32_e32 v76, v76, v140
	v_mul_f32_e32 v77, v77, v141
	v_mul_f32_e32 v78, v78, v142
	v_mul_f32_e32 v79, v79, v143
	s_waitcnt lgkmcnt(8)
	v_mfma_f32_32x32x16_bf16 v[176:191], v[124:127], v[128:131], v[176:191]
	ds_read_b64_tr_b16 v[124:125], v193 offset:30464
	ds_read_b64_tr_b16 v[126:127], v193 offset:31552
	ds_read_b64_tr_b16 v[128:129], v192 offset:7168
	ds_read_b64_tr_b16 v[130:131], v192 offset:7424
	v_mul_f32_e32 v80, v80, v144
	v_mul_f32_e32 v81, v81, v145
	v_mul_f32_e32 v82, v82, v146
	v_mul_f32_e32 v83, v83, v147
	v_mul_f32_e32 v84, v84, v148
	v_mul_f32_e32 v85, v85, v149
	v_mul_f32_e32 v86, v86, v150
	v_mul_f32_e32 v87, v87, v151
	v_mul_f32_e32 v88, v88, v152
	s_waitcnt lgkmcnt(8)
	v_mfma_f32_32x32x16_bf16 v[176:191], v[132:135], v[136:139], v[176:191]
	v_mul_f32_e32 v89, v89, v153
	v_mul_f32_e32 v90, v90, v154
	v_mul_f32_e32 v91, v91, v155
	v_cndmask_b32_e64 v76, 0, v76, s[64:65]
	v_cndmask_b32_e64 v77, 0, v77, s[66:67]
	v_cndmask_b32_e64 v78, 0, v78, s[68:69]
	v_cndmask_b32_e64 v79, 0, v79, s[70:71]
	v_cndmask_b32_e64 v80, 0, v80, s[72:73]
	v_cndmask_b32_e64 v81, 0, v81, s[74:75]
	s_waitcnt lgkmcnt(4)
	v_mfma_f32_32x32x16_bf16 v[176:191], v[116:119], v[120:123], v[176:191]
	v_cndmask_b32_e64 v82, 0, v82, s[76:77]
	v_cndmask_b32_e64 v83, 0, v83, s[78:79]
	v_cndmask_b32_e64 v84, 0, v84, s[80:81]
	v_cndmask_b32_e64 v85, 0, v85, s[82:83]
	v_cndmask_b32_e64 v86, 0, v86, s[84:85]
	v_cndmask_b32_e64 v87, 0, v87, s[86:87]
	v_cndmask_b32_e64 v88, 0, v88, s[88:89]
	v_cndmask_b32_e64 v89, 0, v89, s[90:91]
	v_cndmask_b32_e64 v90, 0, v90, s[92:93]
	s_waitcnt lgkmcnt(0)
	v_mfma_f32_32x32x16_bf16 v[176:191], v[124:127], v[128:131], v[176:191]
	v_cndmask_b32_e64 v91, 0, v91, s[94:95]
	v_cvt_pk_bf16_f32 v156, v76, v77
	v_cvt_pk_bf16_f32 v157, v78, v79
	v_cvt_pk_bf16_f32 v158, v80, v81
	v_cvt_pk_bf16_f32 v159, v82, v83
	v_cvt_pk_bf16_f32 v160, v84, v85
	v_cvt_pk_bf16_f32 v161, v86, v87
	v_cvt_pk_bf16_f32 v162, v88, v89
	v_cvt_pk_bf16_f32 v163, v90, v91

.Lm_g0_8:
	ds_read_b32 v1, v172 offset:0
	ds_read_b64_tr_b16 v[116:117], v193 offset:0
	ds_read_b64_tr_b16 v[118:119], v193 offset:1088
	ds_read_b64_tr_b16 v[120:121], v192 offset:0
	ds_read_b64_tr_b16 v[122:123], v192 offset:256
	ds_read_b64_tr_b16 v[124:125], v193 offset:4352
	ds_read_b64_tr_b16 v[126:127], v193 offset:5440
	ds_read_b64_tr_b16 v[128:129], v192 offset:1024
	ds_read_b64_tr_b16 v[130:131], v192 offset:1280
	ds_read_b64_tr_b16 v[132:133], v193 offset:8704
	ds_read_b64_tr_b16 v[134:135], v193 offset:9792
	ds_read_b64_tr_b16 v[136:137], v192 offset:2048
	ds_read_b64_tr_b16 v[138:139], v192 offset:2304
	s_waitcnt lgkmcnt(12)
	v_exp_f32_e32 v1, v1
	s_nop 0
	v_mul_f32_e32 v176, v176, v1
	v_mul_f32_e32 v177, v177, v1
	v_mul_f32_e32 v178, v178, v1
	v_mul_f32_e32 v179, v179, v1
	v_mul_f32_e32 v180, v180, v1
	v_mul_f32_e32 v181, v181, v1
	v_mul_f32_e32 v182, v182, v1
	v_mul_f32_e32 v183, v183, v1
	v_mul_f32_e32 v184, v184, v1
	v_mul_f32_e32 v185, v185, v1
	v_mul_f32_e32 v186, v186, v1
	v_mul_f32_e32 v187, v187, v1
	v_mul_f32_e32 v188, v188, v1
	v_mul_f32_e32 v189, v189, v1
	v_mul_f32_e32 v190, v190, v1
	v_mul_f32_e32 v191, v191, v1
	s_nop 1
	s_waitcnt lgkmcnt(8)
	v_mfma_f32_32x32x16_bf16 v[176:191], v[116:119], v[120:123], v[176:191]
	ds_read_b64_tr_b16 v[116:117], v193 offset:13056
	ds_read_b64_tr_b16 v[118:119], v193 offset:14144
	ds_read_b64_tr_b16 v[120:121], v192 offset:3072
	ds_read_b64_tr_b16 v[122:123], v192 offset:3328
	global_load_dwordx4 v[4:7], v164, s[38:39]
	s_waitcnt lgkmcnt(8)
	v_mfma_f32_32x32x16_bf16 v[176:191], v[124:127], v[128:131], v[176:191]
	ds_read_b64_tr_b16 v[124:125], v193 offset:17408
	ds_read_b64_tr_b16 v[126:127], v193 offset:18496
	ds_read_b64_tr_b16 v[128:129], v192 offset:4096
	ds_read_b64_tr_b16 v[130:131], v192 offset:4352
	global_load_dwordx4 v[20:23], v164, s[38:39] offset:256
	s_waitcnt lgkmcnt(8)
	v_mfma_f32_32x32x16_bf16 v[176:191], v[132:135], v[136:139], v[176:191]
	ds_read_b64_tr_b16 v[132:133], v193 offset:21760
	ds_read_b64_tr_b16 v[134:135], v193 offset:22848
	ds_read_b64_tr_b16 v[136:137], v192 offset:5120
	ds_read_b64_tr_b16 v[138:139], v192 offset:5376
	global_load_dwordx4 v[8:11], v165, s[38:39]
	s_waitcnt lgkmcnt(8)
	v_mfma_f32_32x32x16_bf16 v[176:191], v[116:119], v[120:123], v[176:191]
	ds_read_b64_tr_b16 v[116:117], v193 offset:26112
	ds_read_b64_tr_b16 v[118:119], v193 offset:27200
	ds_read_b64_tr_b16 v[120:121], v192 offset:6144
	ds_read_b64_tr_b16 v[122:123], v192 offset:6400
	global_load_dwordx4 v[24:27], v165, s[38:39] offset:256
	s_waitcnt lgkmcnt(8)
	v_mfma_f32_32x32x16_bf16 v[176:191], v[124:127], v[128:131], v[176:191]
	ds_read_b64_tr_b16 v[124:125], v193 offset:30464
	ds_read_b64_tr_b16 v[126:127], v193 offset:31552
	ds_read_b64_tr_b16 v[128:129], v192 offset:7168
	ds_read_b64_tr_b16 v[130:131], v192 offset:7424
	global_load_dwordx4 v[12:15], v166, s[38:39]
	s_waitcnt lgkmcnt(8)
	v_mfma_f32_32x32x16_bf16 v[176:191], v[132:135], v[136:139], v[176:191]
	global_load_dwordx4 v[28:31], v166, s[38:39] offset:256
	s_waitcnt lgkmcnt(4)
	v_mfma_f32_32x32x16_bf16 v[176:191], v[116:119], v[120:123], v[176:191]
	global_load_dwordx4 v[16:19], v167, s[38:39]
	s_waitcnt lgkmcnt(0)
	v_mfma_f32_32x32x16_bf16 v[176:191], v[124:127], v[128:131], v[176:191]
	global_load_dwordx4 v[32:35], v167, s[38:39] offset:256
	global_load_dwordx4 v[36:39], v168, s[40:41]
	s_add_u32 s38, s38, s46
	s_addc_u32 s39, s39, s55
	s_add_u32 s40, s40, s47
	s_addc_u32 s41, s41, s55
	s_nop 7
	s_nop 3
	v_cvt_pk_bf16_f32 v140, v176, v177
	v_cvt_pk_bf16_f32 v141, v178, v179
	v_cvt_pk_bf16_f32 v142, v180, v181
	v_cvt_pk_bf16_f32 v143, v182, v183
	v_cvt_pk_bf16_f32 v144, v184, v185
	v_cvt_pk_bf16_f32 v145, v186, v187
	v_cvt_pk_bf16_f32 v146, v188, v189
	v_cvt_pk_bf16_f32 v147, v190, v191
	ds_write_b64 v194, v[140:141] offset:8704
	ds_write_b64 v194, v[142:143] offset:8720
	ds_write_b64 v194, v[144:145] offset:8736
	ds_write_b64 v194, v[146:147] offset:8752
	s_cmp_lt_u32 s50, 63
	s_cbranch_scc0 .Lm_noscan_21
	s_waitcnt vmcnt(9)
	v_mul_f32_e32 v116, s62, v204
	v_mul_f32_e32 v117, s62, v205
	v_add_f32_e32 v118, v116, v117
	s_nop 1
	v_add_f32_dpp v118, v118, v118 row_shr:1 row_mask:0xf bank_mask:0xf bound_ctrl:0
	s_nop 1
	v_add_f32_dpp v118, v118, v118 row_shr:2 row_mask:0xf bank_mask:0xf bound_ctrl:0
	s_nop 1
	v_add_f32_dpp v118, v118, v118 row_shr:4 row_mask:0xf bank_mask:0xf bound_ctrl:0
	s_nop 1
	v_add_f32_dpp v118, v118, v118 row_shr:8 row_mask:0xf bank_mask:0xf bound_ctrl:0
	s_nop 1
	v_add_f32_dpp v118, v118, v118 row_bcast:15 row_mask:0xa bank_mask:0xf
	s_nop 1
	v_add_f32_dpp v118, v118, v118 row_bcast:31 row_mask:0xc bank_mask:0xf
	s_nop 1
	v_readlane_b32 s97, v118, 63
	v_sub_f32_e32 v122, v118, v117
	v_mov_b32_e32 v123, v118
	s_nop 1
	s_cmp_eq_u32 s51, 0
	s_cbranch_scc1 .Lm_scanf_22
	v_sub_f32_e32 v122, s97, v122
	v_sub_f32_e32 v123, s97, v123
	v_fma_f32 v122, v204, s62, v122
	v_fma_f32 v123, v205, s62, v123

.Lm_noscan_21:
.Lm_adone_11:
	s_waitcnt lgkmcnt(0)
	s_barrier
	s_cmp_lt_u32 s3, 4
	s_cbranch_scc0 .Lm_noy_23
	ds_read_b64_tr_b16 v[116:117], v208 offset:0
	ds_read_b64_tr_b16 v[118:119], v208 offset:256
	ds_read_b64_tr_b16 v[120:121], v209 offset:0
	ds_read_b64_tr_b16 v[122:123], v209 offset:1088
	ds_read_b128 v[124:127], v210 offset:0
	ds_read_b64_tr_b16 v[128:129], v208 offset:1024
	ds_read_b64_tr_b16 v[130:131], v208 offset:1280
	ds_read_b64_tr_b16 v[132:133], v209 offset:4352
	ds_read_b64_tr_b16 v[134:135], v209 offset:5440
	ds_read_b128 v[136:139], v210 offset:32
	ds_read_b64_tr_b16 v[140:141], v208 offset:2048
	ds_read_b64_tr_b16 v[142:143], v208 offset:2304
	ds_read_b64_tr_b16 v[144:145], v209 offset:8704
	ds_read_b64_tr_b16 v[146:147], v209 offset:9792
	ds_read_b128 v[148:151], v210 offset:64
	s_waitcnt lgkmcnt(10)
	v_mfma_f32_32x32x16_bf16 v[76:91], v[116:119], v[120:123], 0
	v_mfma_f32_32x32x16_bf16 v[92:107], v[124:127], v[176:179], 0
	ds_read_b64_tr_b16 v[116:117], v208 offset:3072
	ds_read_b64_tr_b16 v[118:119], v208 offset:3328
	ds_read_b64_tr_b16 v[120:121], v209 offset:13056
	ds_read_b64_tr_b16 v[122:123], v209 offset:14144
	ds_read_b128 v[124:127], v210 offset:96
	s_waitcnt lgkmcnt(10)
	v_mfma_f32_32x32x16_bf16 v[76:91], v[128:131], v[132:135], v[76:91]
	v_mfma_f32_32x32x16_bf16 v[92:107], v[136:139], v[180:183], v[92:107]
	ds_read_b64_tr_b16 v[128:129], v208 offset:4096
	ds_read_b64_tr_b16 v[130:131], v208 offset:4352
	ds_read_b64_tr_b16 v[132:133], v209 offset:17408
	ds_read_b64_tr_b16 v[134:135], v209 offset:18496
	ds_read_b128 v[136:139], v210 offset:128
	s_waitcnt lgkmcnt(10)
	v_mfma_f32_32x32x16_bf16 v[76:91], v[140:143], v[144:147], v[76:91]
	v_mfma_f32_32x32x16_bf16 v[92:107], v[148:151], v[184:187], v[92:107]
	ds_read_b64_tr_b16 v[140:141], v208 offset:5120
	ds_read_b64_tr_b16 v[142:143], v208 offset:5376
	ds_read_b64_tr_b16 v[144:145], v209 offset:21760
	ds_read_b64_tr_b16 v[146:147], v209 offset:22848
	ds_read_b128 v[148:151], v210 offset:160
	s_waitcnt lgkmcnt(10)
	v_mfma_f32_32x32x16_bf16 v[76:91], v[116:119], v[120:123], v[76:91]
	v_mfma_f32_32x32x16_bf16 v[92:107], v[124:127], v[188:191], v[92:107]
	ds_read_b64_tr_b16 v[116:117], v208 offset:6144
	ds_read_b64_tr_b16 v[118:119], v208 offset:6400
	ds_read_b64_tr_b16 v[120:121], v209 offset:26112
	ds_read_b64_tr_b16 v[122:123], v209 offset:27200
	ds_read_b128 v[124:127], v210 offset:192
	s_waitcnt lgkmcnt(10)
	v_mfma_f32_32x32x16_bf16 v[76:91], v[128:131], v[132:135], v[76:91]
	v_mfma_f32_32x32x16_bf16 v[92:107], v[136:139], v[192:195], v[92:107]
	ds_read_b64_tr_b16 v[128:129], v208 offset:7168
	ds_read_b64_tr_b16 v[130:131], v208 offset:7424
	ds_read_b64_tr_b16 v[132:133], v209 offset:30464
	ds_read_b64_tr_b16 v[134:135], v209 offset:31552
	ds_read_b128 v[136:139], v210 offset:224
	s_waitcnt lgkmcnt(10)
	v_mfma_f32_32x32x16_bf16 v[76:91], v[140:143], v[144:147], v[76:91]
	v_mfma_f32_32x32x16_bf16 v[92:107], v[148:151], v[196:199], v[92:107]
	s_waitcnt lgkmcnt(5)
	v_mfma_f32_32x32x16_bf16 v[76:91], v[116:119], v[120:123], v[76:91]
	v_mfma_f32_32x32x16_bf16 v[92:107], v[124:127], v[200:203], v[92:107]
	s_waitcnt lgkmcnt(0)
	v_mfma_f32_32x32x16_bf16 v[76:91], v[128:131], v[132:135], v[76:91]
	v_mfma_f32_32x32x16_bf16 v[92:107], v[136:139], v[204:207], v[92:107]

.Lm_w456_37:
	s_cmp_lt_u32 s3, 7
	s_cbranch_scc0 .Lm_g0_32
	ds_read_b128 v[116:119], v216 offset:0
	ds_read_b128 v[120:123], v217 offset:34816
	ds_read_b128 v[128:131], v216 offset:32
	ds_read_b128 v[132:135], v217 offset:34848
	ds_read_b128 v[140:143], v216 offset:64
	ds_read_b128 v[144:147], v217 offset:34880
	ds_read_b128 v[152:155], v216 offset:96
	ds_read_b128 v[156:159], v217 offset:34912
	s_waitcnt lgkmcnt(6)
	v_mfma_f32_32x32x16_bf16 v[76:91], v[116:119], v[120:123], 0
	ds_read_b128 v[116:119], v216 offset:128
	ds_read_b128 v[120:123], v217 offset:34944
	global_load_dwordx4 v[40:43], v164, s[38:39]
	s_waitcnt lgkmcnt(6)
	v_mfma_f32_32x32x16_bf16 v[76:91], v[128:131], v[132:135], v[76:91]
	ds_read_b128 v[128:131], v216 offset:160
	ds_read_b128 v[132:135], v217 offset:34976
	global_load_dwordx4 v[56:59], v164, s[38:39] offset:256
	s_waitcnt lgkmcnt(6)
	v_mfma_f32_32x32x16_bf16 v[76:91], v[140:143], v[144:147], v[76:91]
	ds_read_b128 v[140:143], v216 offset:192
	ds_read_b128 v[144:147], v217 offset:35008
	global_load_dwordx4 v[44:47], v165, s[38:39]
	s_waitcnt lgkmcnt(6)
	v_mfma_f32_32x32x16_bf16 v[76:91], v[152:155], v[156:159], v[76:91]
	ds_read_b128 v[152:155], v216 offset:224
	ds_read_b128 v[156:159], v217 offset:35040
	global_load_dwordx4 v[60:63], v165, s[38:39] offset:256
	s_waitcnt lgkmcnt(6)
	v_mfma_f32_32x32x16_bf16 v[76:91], v[116:119], v[120:123], v[76:91]
	global_load_dwordx4 v[48:51], v166, s[38:39]
	ds_read_b128 v[234:237], v222 offset:2048
	ds_read_b128 v[238:241], v222 offset:2080
	ds_read_b128 v[242:245], v222 offset:2112
	ds_read_b128 v[246:249], v222 offset:2144
	ds_read_b32 v250, v223 offset:2048
	s_waitcnt lgkmcnt(9)
	v_mfma_f32_32x32x16_bf16 v[76:91], v[128:131], v[132:135], v[76:91]
	global_load_dwordx4 v[64:67], v166, s[38:39] offset:256
	s_waitcnt lgkmcnt(7)
	v_mfma_f32_32x32x16_bf16 v[76:91], v[140:143], v[144:147], v[76:91]
	global_load_dwordx4 v[52:55], v167, s[38:39]
	s_waitcnt lgkmcnt(5)
	v_mfma_f32_32x32x16_bf16 v[76:91], v[152:155], v[156:159], v[76:91]
	global_load_dwordx4 v[68:71], v167, s[38:39] offset:256
	global_load_dwordx4 v[72:75], v168, s[40:41]
	s_add_u32 s38, s38, s46
	s_addc_u32 s39, s39, s55
	s_add_u32 s40, s40, s47
	s_addc_u32 s41, s41, s55
	s_waitcnt lgkmcnt(0)
	ds_read_b32 v1, v172 offset:2048
	ds_read_b64_tr_b16 v[116:117], v193 offset:0
	ds_read_b64_tr_b16 v[118:119], v193 offset:1088
	ds_read_b64_tr_b16 v[120:121], v192 offset:0
	ds_read_b64_tr_b16 v[122:123], v192 offset:256
	ds_read_b64_tr_b16 v[124:125], v193 offset:4352
	ds_read_b64_tr_b16 v[126:127], v193 offset:5440
	ds_read_b64_tr_b16 v[128:129], v192 offset:1024
	ds_read_b64_tr_b16 v[130:131], v192 offset:1280
	ds_read_b64_tr_b16 v[132:133], v193 offset:8704
	ds_read_b64_tr_b16 v[134:135], v193 offset:9792
	ds_read_b64_tr_b16 v[136:137], v192 offset:2048
	ds_read_b64_tr_b16 v[138:139], v192 offset:2304
	s_waitcnt lgkmcnt(12)
	v_exp_f32_e32 v1, v1
	s_nop 0
	v_mul_f32_e32 v176, v176, v1
	v_mul_f32_e32 v177, v177, v1
	v_mul_f32_e32 v178, v178, v1
	v_mul_f32_e32 v179, v179, v1
	v_mul_f32_e32 v180, v180, v1
	v_mul_f32_e32 v181, v181, v1
	v_mul_f32_e32 v182, v182, v1
	v_mul_f32_e32 v183, v183, v1
	v_mul_f32_e32 v184, v184, v1
	v_mul_f32_e32 v185, v185, v1
	v_mul_f32_e32 v186, v186, v1
	v_mul_f32_e32 v187, v187, v1
	v_mul_f32_e32 v188, v188, v1
	v_mul_f32_e32 v189, v189, v1
	v_mul_f32_e32 v190, v190, v1
	v_mul_f32_e32 v191, v191, v1
	s_nop 1
	s_cmp_eq_u32 s53, 0
	s_cbranch_scc0 .Lm_sdiag_43
	s_waitcnt lgkmcnt(8)
	v_mfma_f32_32x32x16_bf16 v[176:191], v[116:119], v[120:123], v[176:191]
	ds_read_b64_tr_b16 v[116:117], v193 offset:13056
	ds_read_b64_tr_b16 v[118:119], v193 offset:14144
	ds_read_b64_tr_b16 v[120:121], v192 offset:3072
	ds_read_b64_tr_b16 v[122:123], v192 offset:3328
	v_sub_f32_e32 v140, v234, v250
	v_sub_f32_e32 v141, v235, v250
	v_sub_f32_e32 v142, v236, v250
	v_sub_f32_e32 v143, v237, v250
	v_sub_f32_e32 v144, v238, v250
	v_sub_f32_e32 v145, v239, v250
	v_sub_f32_e32 v146, v240, v250
	s_waitcnt lgkmcnt(8)
	v_mfma_f32_32x32x16_bf16 v[176:191], v[124:127], v[128:131], v[176:191]
	ds_read_b64_tr_b16 v[124:125], v193 offset:17408
	ds_read_b64_tr_b16 v[126:127], v193 offset:18496
	ds_read_b64_tr_b16 v[128:129], v192 offset:4096
	ds_read_b64_tr_b16 v[130:131], v192 offset:4352
	v_sub_f32_e32 v147, v241, v250
	v_sub_f32_e32 v148, v242, v250
	v_sub_f32_e32 v149, v243, v250
	v_sub_f32_e32 v150, v244, v250
	v_sub_f32_e32 v151, v245, v250
	v_sub_f32_e32 v152, v246, v250
	v_sub_f32_e32 v153, v247, v250
	s_waitcnt lgkmcnt(8)
	v_mfma_f32_32x32x16_bf16 v[176:191], v[132:135], v[136:139], v[176:191]
	ds_read_b64_tr_b16 v[132:133], v193 offset:21760
	ds_read_b64_tr_b16 v[134:135], v193 offset:22848
	ds_read_b64_tr_b16 v[136:137], v192 offset:5120
	ds_read_b64_tr_b16 v[138:139], v192 offset:5376
	v_sub_f32_e32 v154, v248, v250
	v_sub_f32_e32 v155, v249, v250
	v_exp_f32_e32 v140, v140
	v_exp_f32_e32 v141, v141
	v_exp_f32_e32 v142, v142
	v_exp_f32_e32 v143, v143
	v_exp_f32_e32 v144, v144
	s_waitcnt lgkmcnt(8)
	v_mfma_f32_32x32x16_bf16 v[176:191], v[116:119], v[120:123], v[176:191]
	ds_read_b64_tr_b16 v[116:117], v193 offset:26112
	ds_read_b64_tr_b16 v[118:119], v193 offset:27200
	ds_read_b64_tr_b16 v[120:121], v192 offset:6144
	ds_read_b64_tr_b16 v[122:123], v192 offset:6400
	v_exp_f32_e32 v145, v145
	v_exp_f32_e32 v146, v146
	v_exp_f32_e32 v147, v147
	v_exp_f32_e32 v148, v148
	v_exp_f32_e32 v149, v149
	v_exp_f32_e32 v150, v150
	v_exp_f32_e32 v151, v151
	s_waitcnt lgkmcnt(8)
	v_mfma_f32_32x32x16_bf16 v[176:191], v[124:127], v[128:131], v[176:191]
	ds_read_b64_tr_b16 v[124:125], v193 offset:30464
	ds_read_b64_tr_b16 v[126:127], v193 offset:31552
	ds_read_b64_tr_b16 v[128:129], v192 offset:7168
	ds_read_b64_tr_b16 v[130:131], v192 offset:7424
	v_exp_f32_e32 v152, v152
	v_exp_f32_e32 v153, v153
	v_exp_f32_e32 v154, v154
	v_exp_f32_e32 v155, v155
	v_mul_f32_e32 v76, v76, v140
	v_mul_f32_e32 v77, v77, v141
	v_mul_f32_e32 v78, v78, v142
	s_waitcnt lgkmcnt(8)
	v_mfma_f32_32x32x16_bf16 v[176:191], v[132:135], v[136:139], v[176:191]
	v_mul_f32_e32 v79, v79, v143
	v_mul_f32_e32 v80, v80, v144
	v_mul_f32_e32 v81, v81, v145
	v_mul_f32_e32 v82, v82, v146
	v_mul_f32_e32 v83, v83, v147
	v_mul_f32_e32 v84, v84, v148
	v_mul_f32_e32 v85, v85, v149
	s_waitcnt lgkmcnt(4)
	v_mfma_f32_32x32x16_bf16 v[176:191], v[116:119], v[120:123], v[176:191]
	v_mul_f32_e32 v86, v86, v150
	v_mul_f32_e32 v87, v87, v151
	v_mul_f32_e32 v88, v88, v152
	v_mul_f32_e32 v89, v89, v153
	v_mul_f32_e32 v90, v90, v154
	v_mul_f32_e32 v91, v91, v155
	v_cvt_pk_bf16_f32 v156, v76, v77
	s_waitcnt lgkmcnt(0)
	v_mfma_f32_32x32x16_bf16 v[176:191], v[124:127], v[128:131], v[176:191]
	v_cvt_pk_bf16_f32 v157, v78, v79
	v_cvt_pk_bf16_f32 v158, v80, v81
	v_cvt_pk_bf16_f32 v159, v82, v83
	v_cvt_pk_bf16_f32 v160, v84, v85
	v_cvt_pk_bf16_f32 v161, v86, v87
	v_cvt_pk_bf16_f32 v162, v88, v89
	v_cvt_pk_bf16_f32 v163, v90, v91
	s_branch .Lm_sjoin_44

.Lm_g0_32:
	ds_read_b32 v1, v172 offset:2048
	ds_read_b64_tr_b16 v[116:117], v193 offset:0
	ds_read_b64_tr_b16 v[118:119], v193 offset:1088
	ds_read_b64_tr_b16 v[120:121], v192 offset:0
	ds_read_b64_tr_b16 v[122:123], v192 offset:256
	ds_read_b64_tr_b16 v[124:125], v193 offset:4352
	ds_read_b64_tr_b16 v[126:127], v193 offset:5440
	ds_read_b64_tr_b16 v[128:129], v192 offset:1024
	ds_read_b64_tr_b16 v[130:131], v192 offset:1280
	ds_read_b64_tr_b16 v[132:133], v193 offset:8704
	ds_read_b64_tr_b16 v[134:135], v193 offset:9792
	ds_read_b64_tr_b16 v[136:137], v192 offset:2048
	ds_read_b64_tr_b16 v[138:139], v192 offset:2304
	s_waitcnt lgkmcnt(12)
	v_exp_f32_e32 v1, v1
	s_nop 0
	v_mul_f32_e32 v176, v176, v1
	v_mul_f32_e32 v177, v177, v1
	v_mul_f32_e32 v178, v178, v1
	v_mul_f32_e32 v179, v179, v1
	v_mul_f32_e32 v180, v180, v1
	v_mul_f32_e32 v181, v181, v1
	v_mul_f32_e32 v182, v182, v1
	v_mul_f32_e32 v183, v183, v1
	v_mul_f32_e32 v184, v184, v1
	v_mul_f32_e32 v185, v185, v1
	v_mul_f32_e32 v186, v186, v1
	v_mul_f32_e32 v187, v187, v1
	v_mul_f32_e32 v188, v188, v1
	v_mul_f32_e32 v189, v189, v1
	v_mul_f32_e32 v190, v190, v1
	v_mul_f32_e32 v191, v191, v1
	s_nop 1
	s_waitcnt lgkmcnt(8)
	v_mfma_f32_32x32x16_bf16 v[176:191], v[116:119], v[120:123], v[176:191]
	ds_read_b64_tr_b16 v[116:117], v193 offset:13056
	ds_read_b64_tr_b16 v[118:119], v193 offset:14144
	ds_read_b64_tr_b16 v[120:121], v192 offset:3072
	ds_read_b64_tr_b16 v[122:123], v192 offset:3328
	global_load_dwordx4 v[40:43], v164, s[38:39]
	s_waitcnt lgkmcnt(8)
	v_mfma_f32_32x32x16_bf16 v[176:191], v[124:127], v[128:131], v[176:191]
	ds_read_b64_tr_b16 v[124:125], v193 offset:17408
	ds_read_b64_tr_b16 v[126:127], v193 offset:18496
	ds_read_b64_tr_b16 v[128:129], v192 offset:4096
	ds_read_b64_tr_b16 v[130:131], v192 offset:4352
	global_load_dwordx4 v[56:59], v164, s[38:39] offset:256
	s_waitcnt lgkmcnt(8)
	v_mfma_f32_32x32x16_bf16 v[176:191], v[132:135], v[136:139], v[176:191]
	ds_read_b64_tr_b16 v[132:133], v193 offset:21760
	ds_read_b64_tr_b16 v[134:135], v193 offset:22848
	ds_read_b64_tr_b16 v[136:137], v192 offset:5120
	ds_read_b64_tr_b16 v[138:139], v192 offset:5376
	global_load_dwordx4 v[44:47], v165, s[38:39]
	s_waitcnt lgkmcnt(8)
	v_mfma_f32_32x32x16_bf16 v[176:191], v[116:119], v[120:123], v[176:191]
	ds_read_b64_tr_b16 v[116:117], v193 offset:26112
	ds_read_b64_tr_b16 v[118:119], v193 offset:27200
	ds_read_b64_tr_b16 v[120:121], v192 offset:6144
	ds_read_b64_tr_b16 v[122:123], v192 offset:6400
	global_load_dwordx4 v[60:63], v165, s[38:39] offset:256
	s_waitcnt lgkmcnt(8)
	v_mfma_f32_32x32x16_bf16 v[176:191], v[124:127], v[128:131], v[176:191]
	ds_read_b64_tr_b16 v[124:125], v193 offset:30464
	ds_read_b64_tr_b16 v[126:127], v193 offset:31552
	ds_read_b64_tr_b16 v[128:129], v192 offset:7168
	ds_read_b64_tr_b16 v[130:131], v192 offset:7424
	global_load_dwordx4 v[48:51], v166, s[38:39]
	s_waitcnt lgkmcnt(8)
	v_mfma_f32_32x32x16_bf16 v[176:191], v[132:135], v[136:139], v[176:191]
	global_load_dwordx4 v[64:67], v166, s[38:39] offset:256
	s_waitcnt lgkmcnt(4)
	v_mfma_f32_32x32x16_bf16 v[176:191], v[116:119], v[120:123], v[176:191]
	global_load_dwordx4 v[52:55], v167, s[38:39]
	s_waitcnt lgkmcnt(0)
	v_mfma_f32_32x32x16_bf16 v[176:191], v[124:127], v[128:131], v[176:191]
	global_load_dwordx4 v[68:71], v167, s[38:39] offset:256
	global_load_dwordx4 v[72:75], v168, s[40:41]
	s_add_u32 s38, s38, s46
	s_addc_u32 s39, s39, s55
	s_add_u32 s40, s40, s47
	s_addc_u32 s41, s41, s55
	s_nop 7
	s_nop 3
	v_cvt_pk_bf16_f32 v140, v176, v177
	v_cvt_pk_bf16_f32 v141, v178, v179
	v_cvt_pk_bf16_f32 v142, v180, v181
	v_cvt_pk_bf16_f32 v143, v182, v183
	v_cvt_pk_bf16_f32 v144, v184, v185
	v_cvt_pk_bf16_f32 v145, v186, v187
	v_cvt_pk_bf16_f32 v146, v188, v189
	v_cvt_pk_bf16_f32 v147, v190, v191
	ds_write_b64 v194, v[140:141] offset:0
	ds_write_b64 v194, v[142:143] offset:16
	ds_write_b64 v194, v[144:145] offset:32
	ds_write_b64 v194, v[146:147] offset:48
	s_cmp_lt_u32 s50, 63
	s_cbranch_scc0 .Lm_noscan_45
	s_waitcnt vmcnt(9)
	v_mul_f32_e32 v116, s62, v204
	v_mul_f32_e32 v117, s62, v205
	v_add_f32_e32 v118, v116, v117
	s_nop 1
	v_add_f32_dpp v118, v118, v118 row_shr:1 row_mask:0xf bank_mask:0xf bound_ctrl:0
	s_nop 1
	v_add_f32_dpp v118, v118, v118 row_shr:2 row_mask:0xf bank_mask:0xf bound_ctrl:0
	s_nop 1
	v_add_f32_dpp v118, v118, v118 row_shr:4 row_mask:0xf bank_mask:0xf bound_ctrl:0
	s_nop 1
	v_add_f32_dpp v118, v118, v118 row_shr:8 row_mask:0xf bank_mask:0xf bound_ctrl:0
	s_nop 1
	v_add_f32_dpp v118, v118, v118 row_bcast:15 row_mask:0xa bank_mask:0xf
	s_nop 1
	v_add_f32_dpp v118, v118, v118 row_bcast:31 row_mask:0xc bank_mask:0xf
	s_nop 1
	v_readlane_b32 s97, v118, 63
	v_sub_f32_e32 v122, v118, v117
	v_mov_b32_e32 v123, v118
	s_nop 1
	s_cmp_eq_u32 s51, 0
	s_cbranch_scc1 .Lm_scanf_46
	v_sub_f32_e32 v122, s97, v122
	v_sub_f32_e32 v123, s97, v123
	v_fma_f32 v122, v204, s62, v122
	v_fma_f32 v123, v205, s62, v123

.Lm_noscan_45:
.Lm_adone_35:
	s_waitcnt lgkmcnt(0)
	s_barrier
	s_cmp_lt_u32 s3, 4
	s_cbranch_scc0 .Lm_noy_47
	ds_read_b64_tr_b16 v[116:117], v208 offset:43008
	ds_read_b64_tr_b16 v[118:119], v208 offset:43264
	ds_read_b64_tr_b16 v[120:121], v209 offset:0
	ds_read_b64_tr_b16 v[122:123], v209 offset:1088
	ds_read_b128 v[124:127], v210 offset:8704
	ds_read_b64_tr_b16 v[128:129], v208 offset:44032
	ds_read_b64_tr_b16 v[130:131], v208 offset:44288
	ds_read_b64_tr_b16 v[132:133], v209 offset:4352
	ds_read_b64_tr_b16 v[134:135], v209 offset:5440
	ds_read_b128 v[136:139], v210 offset:8736
	ds_read_b64_tr_b16 v[140:141], v208 offset:45056
	ds_read_b64_tr_b16 v[142:143], v208 offset:45312
	ds_read_b64_tr_b16 v[144:145], v209 offset:8704
	ds_read_b64_tr_b16 v[146:147], v209 offset:9792
	ds_read_b128 v[148:151], v210 offset:8768
	s_waitcnt lgkmcnt(10)
	v_mfma_f32_32x32x16_bf16 v[76:91], v[116:119], v[120:123], 0
	v_mfma_f32_32x32x16_bf16 v[92:107], v[124:127], v[176:179], 0
	ds_read_b64_tr_b16 v[116:117], v208 offset:46080
	ds_read_b64_tr_b16 v[118:119], v208 offset:46336
	ds_read_b64_tr_b16 v[120:121], v209 offset:13056
	ds_read_b64_tr_b16 v[122:123], v209 offset:14144
	ds_read_b128 v[124:127], v210 offset:8800
	s_waitcnt lgkmcnt(10)
	v_mfma_f32_32x32x16_bf16 v[76:91], v[128:131], v[132:135], v[76:91]
	v_mfma_f32_32x32x16_bf16 v[92:107], v[136:139], v[180:183], v[92:107]
	ds_read_b64_tr_b16 v[128:129], v208 offset:47104
	ds_read_b64_tr_b16 v[130:131], v208 offset:47360
	ds_read_b64_tr_b16 v[132:133], v209 offset:17408
	ds_read_b64_tr_b16 v[134:135], v209 offset:18496
	ds_read_b128 v[136:139], v210 offset:8832
	s_waitcnt lgkmcnt(10)
	v_mfma_f32_32x32x16_bf16 v[76:91], v[140:143], v[144:147], v[76:91]
	v_mfma_f32_32x32x16_bf16 v[92:107], v[148:151], v[184:187], v[92:107]
	ds_read_b64_tr_b16 v[140:141], v208 offset:48128
	ds_read_b64_tr_b16 v[142:143], v208 offset:48384
	ds_read_b64_tr_b16 v[144:145], v209 offset:21760
	ds_read_b64_tr_b16 v[146:147], v209 offset:22848
	ds_read_b128 v[148:151], v210 offset:8864
	s_waitcnt lgkmcnt(10)
	v_mfma_f32_32x32x16_bf16 v[76:91], v[116:119], v[120:123], v[76:91]
	v_mfma_f32_32x32x16_bf16 v[92:107], v[124:127], v[188:191], v[92:107]
	ds_read_b64_tr_b16 v[116:117], v208 offset:49152
	ds_read_b64_tr_b16 v[118:119], v208 offset:49408
	ds_read_b64_tr_b16 v[120:121], v209 offset:26112
	ds_read_b64_tr_b16 v[122:123], v209 offset:27200
	ds_read_b128 v[124:127], v210 offset:8896
	s_waitcnt lgkmcnt(10)
	v_mfma_f32_32x32x16_bf16 v[76:91], v[128:131], v[132:135], v[76:91]
	v_mfma_f32_32x32x16_bf16 v[92:107], v[136:139], v[192:195], v[92:107]
	ds_read_b64_tr_b16 v[128:129], v208 offset:50176
	ds_read_b64_tr_b16 v[130:131], v208 offset:50432
	ds_read_b64_tr_b16 v[132:133], v209 offset:30464
	ds_read_b64_tr_b16 v[134:135], v209 offset:31552
	ds_read_b128 v[136:139], v210 offset:8928
	s_waitcnt lgkmcnt(10)
	v_mfma_f32_32x32x16_bf16 v[76:91], v[140:143], v[144:147], v[76:91]
	v_mfma_f32_32x32x16_bf16 v[92:107], v[148:151], v[196:199], v[92:107]
	s_waitcnt lgkmcnt(5)
	v_mfma_f32_32x32x16_bf16 v[76:91], v[116:119], v[120:123], v[76:91]
	v_mfma_f32_32x32x16_bf16 v[92:107], v[124:127], v[200:203], v[92:107]
	s_waitcnt lgkmcnt(0)
	v_mfma_f32_32x32x16_bf16 v[76:91], v[128:131], v[132:135], v[76:91]
	v_mfma_f32_32x32x16_bf16 v[92:107], v[136:139], v[204:207], v[92:107]
